# fold phase meta-token dot: also hoist the 5 serialized dwordx2 weight loads to the front and drop the per-output store-ack waits, on top of v46
# baseline (speedup 1.0000x reference)
; __device__ __forceinline__ bf16_t f2bf(float f) { return (bf16_t)(cvt_pk_bf16(f, 0.f) & 0xffffu); }
; __device__ __forceinline__ int otid() { int t = threadIdx.x; asm volatile("" : "+v"(t)); return t; }
; __device__ void conv_mixer_item(const Params& p, int l, int it, float* lds) {
;     ...
;         const int kb = it & 1, jb = it >> 1, k = kb * 512 + otid();
;         const float* src = p.w_in + (size_t)l * 1024 * 4112 + (size_t)k * 4112 + 2048; float a[16];
; #pragma unroll
;         for (int q = 0; q < 4; ++q) { const f32x4 v = *(const f32x4*)(src + 4 * q); a[4 * q] = v[0]; a[4 * q + 1] = v[1]; a[4 * q + 2] = v[2]; a[4 * q + 3] = v[3]; }
;         const float* wa = p.w_alpha + (size_t)l * 16 * 256; const float g1 = p.norm1[(size_t)l * DM + k];
;         for (int jj = 0; jj < 8; ++jj) { const int j = jb * 8 + jj; float s = 0.f;
; #pragma unroll
;             for (int r = 0; r < 16; ++r) s += a[r] * wa[r * 256 + j];
;             W[W_IN + (size_t)(C_GL + j) * 1024 + k] = f2bf(s * g1); }
.LBB0_146:
	s_and_b64 vcc, exec, s[40:41]
	s_cbranch_vccz .LBB0_148
	v_mov_b32_e32 v0, v228
	s_and_b32 s22, s10, 0x200
	s_and_b32 s33, s12, 0x7f8
	v_add_u32_e32 v10, s22, v0
	v_ashrrev_i32_e32 v11, 31, v10
	s_waitcnt lgkmcnt(0)
	v_lshl_add_u64 v[2:3], v[10:11], 2, s[68:69]
	global_load_dword v0, v[2:3], off
	v_mov_b64_e32 v[2:3], s[88:89]
	s_movk_i32 s22, 0x4040
	v_mad_i64_i32 v[2:3], s[22:23], v10, s22, v[2:3]
	s_mov_b64 s[22:23], 0x2000
	s_nop 0
	v_lshl_add_u64 v[6:7], v[2:3], 0, s[22:23]
	v_add_co_u32_e32 v2, vcc, 0x2000, v2
	s_lshl_b32 s22, s33, 2
	s_nop 0
	v_addc_co_u32_e32 v3, vcc, 0, v3, vcc
	global_load_dwordx4 v[42:45], v[2:3], off
	global_load_dwordx4 v[38:41], v[6:7], off offset:16
	s_nop 0
	global_load_dwordx4 v[2:5], v[6:7], off offset:32
	s_nop 0
	global_load_dwordx4 v[6:9], v[6:7], off offset:48
	s_add_u32 s40, s6, s22
	s_addc_u32 s41, s7, 0
	s_add_i32 s30, s33, 0x400
	v_lshl_add_u64 v[98:99], v[10:11], 1, s[18:19]
	s_waitcnt vmcnt(0)
	v_mov_b32_e32 v106, v45
	v_mov_b32_e32 v104, v41
	v_mov_b32_e32 v102, v5
	v_mov_b32_e32 v5, s22
	global_load_dwordx4 v[46:49], v5, s[6:7] offset:-4080
	global_load_dwordx4 v[76:79], v5, s[6:7] offset:-4096
	global_load_dwordx4 v[50:53], v5, s[6:7] offset:-3056
	global_load_dwordx4 v[80:83], v5, s[6:7] offset:-3072
	global_load_dwordx4 v[58:61], v5, s[6:7] offset:-2032
	global_load_dwordx4 v[86:89], v5, s[6:7] offset:-2048
	global_load_dwordx4 v[66:69], v5, s[6:7] offset:-1008
	global_load_dwordx4 v[90:93], v5, s[6:7] offset:-1024
	global_load_dwordx4 v[108:111], v5, s[6:7]
	global_load_dwordx4 v[54:57], v5, s[6:7] offset:1040
	global_load_dwordx4 v[112:115], v5, s[6:7] offset:1024
	global_load_dwordx4 v[62:65], v5, s[6:7] offset:2064
	global_load_dwordx4 v[116:119], v5, s[6:7] offset:2048
	s_lshl_b32 s22, s30, 2
	global_load_dwordx4 v[70:73], v5, s[6:7] offset:3088
	global_load_dwordx4 v[120:123], v5, s[6:7] offset:3072
	v_mov_b32_e32 v5, s22
	global_load_dwordx2 v[142:143], v5, s[6:7]
	s_add_u32 s22, s40, 0x1400
	s_addc_u32 s23, s41, 0
	v_mov_b32_e32 v100, v9
	global_load_dwordx4 v[10:13], v1, s[22:23] offset:16
	global_load_dwordx4 v[144:147], v230, s[40:41] offset:1024
	s_add_u32 s22, s40, 0x1800
	s_addc_u32 s23, s41, 0
	global_load_dwordx4 v[14:17], v1, s[22:23] offset:16
	global_load_dwordx4 v[148:151], v230, s[40:41] offset:2048
	s_add_u32 s22, s40, 0x1c00
	s_addc_u32 s23, s41, 0
	global_load_dwordx4 v[18:21], v1, s[22:23] offset:16
	global_load_dwordx4 v[94:97], v230, s[40:41] offset:3072
	s_add_u32 s22, s40, 0x2000
	s_addc_u32 s23, s41, 0
	global_load_dwordx4 v[22:25], v1, s[22:23] offset:16
	global_load_dwordx4 v[124:127], v231, s[40:41]
	s_add_u32 s22, s40, 0x2400
	s_addc_u32 s23, s41, 0
	global_load_dwordx4 v[26:29], v1, s[22:23] offset:16
	global_load_dwordx4 v[128:131], v231, s[40:41] offset:1024
	s_add_u32 s22, s40, 0x2800
	s_addc_u32 s23, s41, 0
	global_load_dwordx4 v[30:33], v1, s[22:23] offset:16
	global_load_dwordx4 v[132:135], v231, s[40:41] offset:2048
	s_add_u32 s22, s40, 0x2c00
	s_addc_u32 s23, s41, 0
	global_load_dwordx4 v[34:37], v1, s[22:23] offset:16
	global_load_dwordx4 v[136:139], v231, s[40:41] offset:3072
	s_add_i32 s100, s33, 0x402
	s_lshl_b32 s100, s100, 2
	v_mov_b32_e32 v162, s100
	s_add_i32 s100, s33, 0x404
	s_lshl_b32 s100, s100, 2
	v_mov_b32_e32 v163, s100
	s_add_i32 s100, s33, 0x406
	s_lshl_b32 s100, s100, 2
	v_mov_b32_e32 v164, s100
	global_load_dwordx2 v[152:153], v162, s[6:7]
	s_or_b32 s86, s12, 4
	s_lshl_b64 s[100:101], s[86:87], 2
	s_add_u32 s100, s6, s100
	s_addc_u32 s101, s7, s101
	global_load_dwordx2 v[154:155], v1, s[100:101]
	global_load_dwordx2 v[156:157], v163, s[6:7]
	s_or_b32 s86, s12, 6
	s_lshl_b64 s[100:101], s[86:87], 2
	s_add_u32 s100, s6, s100
	s_addc_u32 s101, s7, s101
	global_load_dwordx2 v[158:159], v1, s[100:101]
	global_load_dwordx2 v[160:161], v164, s[6:7]
	s_waitcnt vmcnt(34)
	v_pk_fma_f32 v[46:47], v[42:43], v[46:47], 0 op_sel_hi:[0,1,0]
	s_waitcnt vmcnt(33)
	v_pk_fma_f32 v[140:141], v[42:43], v[76:77], 0 op_sel_hi:[0,1,0]
	s_waitcnt vmcnt(31)
	v_pk_fma_f32 v[140:141], v[42:43], v[80:81], v[140:141] op_sel:[1,0,0]
	v_pk_fma_f32 v[46:47], v[42:43], v[50:51], v[46:47] op_sel:[1,0,0]
	s_waitcnt vmcnt(29)
	v_pk_fma_f32 v[140:141], v[44:45], v[86:87], v[140:141] op_sel_hi:[0,1,1]
	s_waitcnt vmcnt(27)
	v_pk_fma_f32 v[140:141], v[106:107], v[90:91], v[140:141] op_sel_hi:[0,1,1]
	s_waitcnt vmcnt(26)
	v_pk_fma_f32 v[140:141], v[38:39], v[108:109], v[140:141] op_sel_hi:[0,1,1]
	s_waitcnt vmcnt(24)
	v_pk_fma_f32 v[140:141], v[38:39], v[112:113], v[140:141] op_sel:[1,0,0]
	v_pk_fma_f32 v[46:47], v[44:45], v[58:59], v[46:47] op_sel_hi:[0,1,1]
	s_waitcnt vmcnt(22)
	v_pk_fma_f32 v[140:141], v[40:41], v[116:117], v[140:141] op_sel_hi:[0,1,1]
	s_waitcnt vmcnt(20)
	v_pk_fma_f32 v[140:141], v[104:105], v[120:121], v[140:141] op_sel_hi:[0,1,1]
	s_waitcnt vmcnt(19)
	v_pk_fma_f32 v[140:141], v[2:3], v[142:143], v[140:141] op_sel_hi:[0,1,1]
	v_pk_fma_f32 v[46:47], v[106:107], v[66:67], v[46:47] op_sel_hi:[0,1,1]
	s_waitcnt vmcnt(17)
	v_pk_fma_f32 v[140:141], v[2:3], v[144:145], v[140:141] op_sel:[1,0,0]
	s_waitcnt vmcnt(15)
	v_pk_fma_f32 v[140:141], v[4:5], v[148:149], v[140:141] op_sel_hi:[0,1,1]
	s_waitcnt vmcnt(13)
	v_pk_fma_f32 v[140:141], v[102:103], v[94:95], v[140:141] op_sel_hi:[0,1,1]
	s_waitcnt vmcnt(11)
; __device__ __forceinline__ bf16_t f2bf(float f) { return (bf16_t)(cvt_pk_bf16(f, 0.f) & 0xffffu); }
; __device__ void conv_mixer_item(const Params& p, int l, int it, float* lds) {
;     ...
;         const float* wa = p.w_alpha + (size_t)l * 16 * 256; const float g1 = p.norm1[(size_t)l * DM + k];
;         for (int jj = 0; jj < 8; ++jj) { const int j = jb * 8 + jj; float s = 0.f;
; #pragma unroll
;             for (int r = 0; r < 16; ++r) s += a[r] * wa[r * 256 + j];
;             W[W_IN + (size_t)(C_GL + j) * 1024 + k] = f2bf(s * g1); }
	v_pk_fma_f32 v[140:141], v[6:7], v[124:125], v[140:141] op_sel_hi:[0,1,1]
	s_waitcnt vmcnt(9)
	v_pk_fma_f32 v[140:141], v[6:7], v[128:129], v[140:141] op_sel:[1,0,0]
	s_lshl_b32 s86, s30, 11
	s_waitcnt vmcnt(7)
	v_pk_fma_f32 v[140:141], v[8:9], v[132:133], v[140:141] op_sel_hi:[0,1,1]
	s_lshl_b32 s40, s33, 11
	s_add_i32 s22, s40, 0x200800
	s_mov_b32 s23, s87
	v_lshl_add_u64 v[80:81], v[98:99], 0, s[22:23]
	s_add_i32 s23, s33, 0x402
	s_lshl_b32 s22, s23, 2
	s_waitcnt vmcnt(0)
	v_pk_fma_f32 v[74:75], v[100:101], v[136:137], v[140:141] op_sel_hi:[0,1,1]
	v_pk_mul_f32 v[74:75], v[0:1], v[74:75] op_sel_hi:[0,1]
	v_cvt_pk_bf16_f32 v5, v74, v75
	v_lshl_add_u64 v[74:75], v[98:99], 0, s[86:87]
	global_store_short v[74:75], v5, off
	global_store_short_d16_hi v[80:81], v5, off
	v_mov_b32_e32 v5, s22
	v_pk_fma_f32 v[74:75], v[42:43], v[78:79], 0 op_sel_hi:[0,1,0]
	s_nop 0
	v_pk_fma_f32 v[74:75], v[42:43], v[82:83], v[74:75] op_sel:[1,0,0]
	s_lshl_b32 s86, s23, 11
	v_pk_fma_f32 v[74:75], v[44:45], v[88:89], v[74:75] op_sel_hi:[0,1,1]
	v_pk_fma_f32 v[74:75], v[106:107], v[92:93], v[74:75] op_sel_hi:[0,1,1]
	v_pk_fma_f32 v[74:75], v[38:39], v[110:111], v[74:75] op_sel_hi:[0,1,1]
	v_pk_fma_f32 v[74:75], v[38:39], v[114:115], v[74:75] op_sel:[1,0,0]
	s_add_i32 s22, s40, 0x201800
	v_pk_fma_f32 v[74:75], v[40:41], v[118:119], v[74:75] op_sel_hi:[0,1,1]
	v_pk_fma_f32 v[74:75], v[104:105], v[122:123], v[74:75] op_sel_hi:[0,1,1]
	s_mov_b32 s23, s87
	s_nop 0
	v_pk_fma_f32 v[74:75], v[2:3], v[152:153], v[74:75] op_sel_hi:[0,1,1]
	v_pk_fma_f32 v[74:75], v[2:3], v[146:147], v[74:75] op_sel:[1,0,0]
	v_lshl_add_u64 v[76:77], v[98:99], 0, s[22:23]
	v_pk_fma_f32 v[74:75], v[4:5], v[150:151], v[74:75] op_sel_hi:[0,1,1]
	v_pk_fma_f32 v[74:75], v[102:103], v[96:97], v[74:75] op_sel_hi:[0,1,1]
	v_pk_fma_f32 v[74:75], v[6:7], v[126:127], v[74:75] op_sel_hi:[0,1,1]
	v_pk_fma_f32 v[74:75], v[6:7], v[130:131], v[74:75] op_sel:[1,0,0]
	s_nop 0
	v_pk_fma_f32 v[74:75], v[8:9], v[134:135], v[74:75] op_sel_hi:[0,1,1]
	v_pk_fma_f32 v[74:75], v[100:101], v[138:139], v[74:75] op_sel_hi:[0,1,1]
	v_pk_mul_f32 v[74:75], v[0:1], v[74:75] op_sel_hi:[0,1]
	v_cvt_pk_bf16_f32 v5, v74, v75
	v_lshl_add_u64 v[74:75], v[98:99], 0, s[86:87]
	s_or_b32 s86, s12, 4
	s_lshl_b64 s[22:23], s[86:87], 2
	s_add_u32 s22, s6, s22
	global_store_short v[74:75], v5, off
	global_store_short_d16_hi v[76:77], v5, off
	s_addc_u32 s23, s7, s23
	s_nop 0
	s_add_i32 s23, s33, 0x404
	s_lshl_b32 s22, s23, 2
	v_mov_b32_e32 v5, s22
	s_lshl_b32 s86, s23, 11
	s_add_i32 s22, s40, 0x202800
	s_mov_b32 s23, s87
	s_nop 0
	v_pk_fma_f32 v[46:47], v[38:39], v[154:155], v[46:47] op_sel_hi:[0,1,1]
	s_nop 0
	v_pk_fma_f32 v[46:47], v[38:39], v[54:55], v[46:47] op_sel:[1,0,0]
	s_nop 0
	v_pk_fma_f32 v[46:47], v[40:41], v[62:63], v[46:47] op_sel_hi:[0,1,1]
	v_pk_fma_f32 v[46:47], v[104:105], v[70:71], v[46:47] op_sel_hi:[0,1,1]
	s_nop 0
	v_pk_fma_f32 v[46:47], v[2:3], v[156:157], v[46:47] op_sel_hi:[0,1,1]
	v_pk_fma_f32 v[10:11], v[2:3], v[10:11], v[46:47] op_sel:[1,0,0]
	s_nop 0
	v_pk_fma_f32 v[10:11], v[4:5], v[14:15], v[10:11] op_sel_hi:[0,1,1]
	v_pk_fma_f32 v[10:11], v[102:103], v[18:19], v[10:11] op_sel_hi:[0,1,1]
	v_pk_fma_f32 v[10:11], v[6:7], v[22:23], v[10:11] op_sel_hi:[0,1,1]
	v_pk_fma_f32 v[10:11], v[6:7], v[26:27], v[10:11] op_sel:[1,0,0]
	v_lshl_add_u64 v[14:15], v[98:99], 0, s[22:23]
	v_pk_fma_f32 v[10:11], v[8:9], v[30:31], v[10:11] op_sel_hi:[0,1,1]
	v_pk_fma_f32 v[10:11], v[100:101], v[34:35], v[10:11] op_sel_hi:[0,1,1]
	v_pk_mul_f32 v[10:11], v[0:1], v[10:11] op_sel_hi:[0,1]
	v_cvt_pk_bf16_f32 v5, v10, v11
	v_lshl_add_u64 v[10:11], v[98:99], 0, s[86:87]
	s_or_b32 s86, s12, 6
	s_lshl_b64 s[22:23], s[86:87], 2
	s_add_u32 s22, s6, s22
	global_store_short v[10:11], v5, off
	global_store_short_d16_hi v[14:15], v5, off
	s_addc_u32 s23, s7, s23
	s_nop 0
	v_pk_fma_f32 v[10:11], v[42:43], v[48:49], 0 op_sel_hi:[0,1,0]
	v_pk_fma_f32 v[10:11], v[42:43], v[52:53], v[10:11] op_sel:[1,0,0]
	s_addk_i32 s33, 0x406
	v_pk_fma_f32 v[10:11], v[44:45], v[60:61], v[10:11] op_sel_hi:[0,1,1]
	s_lshl_b32 s22, s33, 2
	v_pk_fma_f32 v[10:11], v[106:107], v[68:69], v[10:11] op_sel_hi:[0,1,1]
	v_mov_b32_e32 v5, s22
	s_lshl_b32 s86, s33, 11
	s_add_i32 s22, s40, 0x203800
	s_mov_b32 s23, s87
	s_nop 0
	v_pk_fma_f32 v[10:11], v[38:39], v[158:159], v[10:11] op_sel_hi:[0,1,1]
	s_nop 0
	v_pk_fma_f32 v[10:11], v[38:39], v[56:57], v[10:11] op_sel:[1,0,0]
	s_nop 0
	v_pk_fma_f32 v[10:11], v[40:41], v[64:65], v[10:11] op_sel_hi:[0,1,1]
	v_pk_fma_f32 v[10:11], v[104:105], v[72:73], v[10:11] op_sel_hi:[0,1,1]
	s_nop 0
	v_pk_fma_f32 v[10:11], v[2:3], v[160:161], v[10:11] op_sel_hi:[0,1,1]
	v_pk_fma_f32 v[2:3], v[2:3], v[12:13], v[10:11] op_sel:[1,0,0]
	s_nop 0
	v_pk_fma_f32 v[2:3], v[4:5], v[16:17], v[2:3] op_sel_hi:[0,1,1]
	v_pk_fma_f32 v[2:3], v[102:103], v[20:21], v[2:3] op_sel_hi:[0,1,1]
	v_pk_fma_f32 v[2:3], v[6:7], v[24:25], v[2:3] op_sel_hi:[0,1,1]
	v_pk_fma_f32 v[2:3], v[6:7], v[28:29], v[2:3] op_sel:[1,0,0]
	v_lshl_add_u64 v[4:5], v[98:99], 0, s[22:23]
	v_pk_fma_f32 v[2:3], v[8:9], v[32:33], v[2:3] op_sel_hi:[0,1,1]
	v_pk_fma_f32 v[2:3], v[100:101], v[36:37], v[2:3] op_sel_hi:[0,1,1]
	v_pk_mul_f32 v[2:3], v[0:1], v[2:3] op_sel_hi:[0,1]
	v_cvt_pk_bf16_f32 v0, v2, v3
	v_lshl_add_u64 v[2:3], v[98:99], 0, s[86:87]
	global_store_short v[2:3], v0, off
	global_store_short_d16_hi v[4:5], v0, off
